# P1: GEMM tiles on workgroups 0..199 (4 rounds), weight copies + S5 tables on workgroups 200..255 for the whole phase (HBM-bound copies overlap the MFMA-bound tiles)
# speedup vs baseline: 1.0275x; 1.0275x over previous
.LBB0_147:
	s_or_b64 exec, exec, s[0:1]
	v_mov_b32_e32 v8, v252
	s_waitcnt lgkmcnt(0)
	s_barrier
	s_cmpk_gt_i32 s50, 0xc7
	s_nop 0
	v_readfirstlane_b32 s10, v8
	s_cbranch_scc0 .LBB0_150
	s_mov_b64 s[6:7], 0
	s_mov_b64 s[4:5], 0
	s_branch .LBB0_151
	s_mov_b64 s[6:7], 0
	s_cmpk_gt_u32 s50, 0x317
	s_mov_b64 s[4:5], 0
	s_cbranch_scc1 .LBB0_151
	s_add_i32 s0, s50, 0xfffffd00
	s_lshr_b32 s1, s0, 2
	s_add_i32 s3, s1, 2
	s_cmp_lt_u32 s0, 16
	s_cselect_b32 s30, s1, s3
	s_and_b32 s0, s50, 3
	s_or_b32 s0, s0, 32
	s_mov_b64 s[4:5], -1
	s_branch .LBB0_151

.LBB0_159:
	s_add_i32 s61, s61, 1
	s_mov_b32 s1, 0
	s_mov_b32 s4, 0
	s_add_i32 s4, s4, s1
	s_mul_i32 s1, s61, 0xc8
	s_add_u32 s18, s1, s50
	s_addc_u32 s19, s4, s33
	v_cmp_gt_i64_e32 vcc, s[18:19], v[146:147]
	s_mov_b64 s[20:21], -1
	s_cbranch_vccz .LBB0_162
	s_add_i32 s1, s18, 0xfffffd00
	s_mov_b64 s[20:21], 0
	s_cmp_gt_i32 s1, 23
	s_mov_b64 s[46:47], 0
	s_cbranch_scc1 .LBB0_162
	s_ashr_i32 s1, s1, 2
	s_add_i32 s4, s1, 2
	s_cmp_lt_i32 s1, 4
	s_cselect_b32 s12, s1, s4
	s_and_b32 s1, s18, 3
	s_or_b32 s10, s1, 32
	s_mov_b64 s[46:47], -1

.LBB0_219:
	s_add_u32 s0, s92, 0x180000
	v_writelane_b32 v255, s0, 11
	s_addc_u32 s0, s93, 0
	v_writelane_b32 v255, s0, 12
	s_add_u32 s0, s92, 0x1a00000
	s_addc_u32 s1, s93, 0
	s_add_u32 s10, s92, 0x2200000
	v_writelane_b32 v255, s0, 13
	s_addc_u32 s11, s93, 0
	s_nop 0
	v_writelane_b32 v255, s1, 14
	s_add_u32 s0, s92, 0x2400000
	s_addc_u32 s1, s93, 0
	v_writelane_b32 v255, s0, 15
	s_nop 1
	v_writelane_b32 v255, s1, 16
	s_add_u32 s0, s92, 0x2600000
	s_addc_u32 s1, s93, 0
	v_writelane_b32 v255, s0, 17
	s_nop 1
	v_writelane_b32 v255, s1, 18
	s_add_u32 s0, s92, 0x2a00000
	s_addc_u32 s1, s93, 0
	v_writelane_b32 v255, s0, 19
	s_nop 1
	v_writelane_b32 v255, s1, 20
	s_add_u32 s0, s92, 0x3200000
	s_addc_u32 s1, s93, 0
	v_writelane_b32 v255, s0, 21
	s_add_u32 s40, s92, 0x10c00000
	s_addc_u32 s41, s93, 0
	v_writelane_b32 v255, s1, 22
	s_cmp_gt_i32 s50, 199
	v_readlane_b32 s4, v255, 9
	s_cselect_b64 s[0:1], -1, 0
	v_readlane_b32 s5, v255, 10
	s_or_b64 s[0:1], s[0:1], s[4:5]
	v_writelane_b32 v255, s72, 23
	s_and_b64 vcc, exec, s[0:1]
	s_nop 0
	v_writelane_b32 v255, s73, 24
	s_cbranch_vccz .LBB0_380
	s_add_u32 s76, s92, 0x106000
	v_readlane_b32 s5, v255, 4
	v_readlane_b32 s0, v255, 9
	s_addc_u32 s77, s93, 0
	s_add_i32 s4, s5, 0xfffff9c0
	v_readlane_b32 s1, v255, 10
	s_and_b64 s[0:1], s[0:1], exec
	v_mov_b32_e32 v133, v252
	s_cselect_b32 s23, s5, s4
	v_readfirstlane_b32 s0, v133
	s_ashr_i32 s24, s0, 6
	v_and_b32_e32 v132, 63, v133
	s_add_i32 s22, s24, s23
	s_cmpk_lt_i32 s22, 0x2140
	v_lshrrev_b32_e32 v139, 4, v132
	v_lshlrev_b32_e32 v0, 2, v132
	s_cbranch_scc1 .LBB0_223
	s_waitcnt vmcnt(0)
	v_lshrrev_b32_e32 v64, 4, v132
	v_and_b32_e32 v134, 60, v0
	v_mov_b32_e32 v135, 0
	v_or_b32_e32 v140, 4, v64
	v_or_b32_e32 v141, 8, v64
	v_or_b32_e32 v142, 12, v64
	v_or_b32_e32 v143, 16, v64
	v_or_b32_e32 v144, 20, v64
	v_or_b32_e32 v145, 24, v64
	v_or_b32_e32 v146, 28, v64
	v_or_b32_e32 v147, 32, v64
	v_or_b32_e32 v148, 36, v64
	s_waitcnt lgkmcnt(0)
	v_or_b32_e32 v149, 40, v64
	v_or_b32_e32 v150, 44, v64
	v_or_b32_e32 v151, 48, v64
	v_or_b32_e32 v152, 52, v64
	v_or_b32_e32 v153, 56, v64
	v_or_b32_e32 v154, 60, v64
	s_cbranch_execz .LBB0_224
	s_waitcnt vmcnt(0)
	v_mov_b32_e32 v139, v64
	s_branch .LBB0_248

.LBB0_248:
	s_mul_i32 s0, s24, 0x4100
	s_add_i32 s4, s0, 0
	v_readlane_b32 s0, v255, 9
	v_readlane_b32 s1, v255, 10
	s_and_b64 s[0:1], s[0:1], exec
	v_readlane_b32 s0, v255, 5
	v_lshlrev_b32_e32 v82, 3, v132
	s_cselect_b32 s30, s0, 0x1c0
	v_mov_b32_e32 v64, s4
	s_movk_i32 s0, 0x104
	v_and_b32_e32 v138, 56, v82
	v_mad_u32_u24 v157, v138, s0, v64
	v_lshrrev_b32_e32 v64, 1, v133
	v_lshrrev_b32_e32 v156, 3, v132
	v_and_b32_e32 v64, 16, v64
	v_lshl_add_u32 v65, v134, 2, s4
	v_mul_i32_i24_e32 v66, 0x104, v139
	v_mul_i32_i24_e32 v67, 0x104, v140
	v_mul_i32_i24_e32 v68, 0x104, v141
	v_mul_i32_i24_e32 v69, 0x104, v142
	v_mul_i32_i24_e32 v70, 0x104, v143
	v_mul_i32_i24_e32 v71, 0x104, v144
	v_mul_i32_i24_e32 v72, 0x104, v145
	v_mul_i32_i24_e32 v73, 0x104, v146
	v_mul_i32_i24_e32 v74, 0x104, v147
	v_mul_i32_i24_e32 v75, 0x104, v148
	s_waitcnt lgkmcnt(0)
	v_mul_i32_i24_e32 v76, 0x104, v149
	v_mul_i32_i24_e32 v77, 0x104, v150
	v_mul_i32_i24_e32 v78, 0x104, v151
	v_mul_i32_i24_e32 v79, 0x104, v152
	v_mul_i32_i24_e32 v80, 0x104, v153
	v_mul_i32_i24_e32 v81, 0x104, v154
	v_and_or_b32 v158, v156, 3, v64
	v_lshl_add_u32 v155, v132, 2, s4
	v_mov_b32_e32 v137, 0
	v_or_b32_e32 v159, 8, v156
	v_or_b32_e32 v160, 4, v158
	v_or_b32_e32 v161, 16, v156
	v_or_b32_e32 v162, 8, v158
	v_or_b32_e32 v163, 24, v156
	v_or_b32_e32 v164, 12, v158
	v_or_b32_e32 v165, 32, v156
	v_or_b32_e32 v166, 32, v158
	v_or_b32_e32 v167, 40, v156
	v_or_b32_e32 v168, 36, v158
	v_or_b32_e32 v169, 48, v156
	v_or_b32_e32 v170, 40, v158
	v_or_b32_e32 v171, 56, v156
	v_or_b32_e32 v172, 44, v158
	v_mov_b32_e32 v173, 0xc000
	v_mov_b32_e32 v174, 0x18000
	v_mov_b32_e32 v175, 0x24000
	v_add_u32_e32 v176, v65, v66
	v_add_u32_e32 v177, v65, v67
	v_add_u32_e32 v178, v65, v68
	v_add_u32_e32 v179, v65, v69
	v_add_u32_e32 v180, v65, v70
	v_add_u32_e32 v181, v65, v71
	v_add_u32_e32 v182, v65, v72
	v_add_u32_e32 v183, v65, v73
	v_add_u32_e32 v184, v65, v74
	v_add_u32_e32 v185, v65, v75
	v_add_u32_e32 v186, v65, v76
	v_add_u32_e32 v187, v65, v77
	v_add_u32_e32 v188, v65, v78
	v_add_u32_e32 v189, v65, v79
	v_add_u32_e32 v190, v65, v80
	v_add_u32_e32 v191, v65, v81
	s_mov_b32 s27, s22
	s_mov_b64 s[44:45], s[66:67]
	v_readlane_b32 s1, v255, 6
	s_branch .LBB0_251
